# grid barrier poll loops without s_sleep (tighter release polling)
# speedup vs baseline: 1.0070x; 1.0030x over previous
; __device__ __forceinline__ unsigned xb_ld(unsigned* p)              { return __hip_atomic_load(p, __ATOMIC_RELAXED, __HIP_MEMORY_SCOPE_AGENT); }
; __device__ __forceinline__ void xcd_barrier_complete(unsigned* bar, unsigned x, unsigned& nloc, unsigned& nx) {
;     ...
;     for (;;) {
;         sum = 0u; cnt = 0u; mine = 0u;
; #pragma unroll
;         for (unsigned j = 0; j < 16; ++j) { const unsigned c = xb_ld(&bar[XB_XCNT(j)]); sum += c; cnt += (c > 0u) ? 1u : 0u; mine = (j == x) ? c : mine; }
;         if (sum == G) break;
;         __builtin_amdgcn_s_sleep(1);
;         if ((++sp & 255u) == 0u) { if (xb_ld(&bar[XB_TMO])) break; if (sp > XB_SPIN_CAP) { atomicAdd(&bar[XB_TMO], 1u); break; } }
;     }
.LBB0_1024:
	global_load_dword v16, v1, s[90:91] offset:1024 sc1
	global_load_dword v0, v1, s[90:91] offset:1280 sc1
	s_waitcnt lgkmcnt(0)
	global_load_dword v2, v1, s[90:91] offset:1536 sc1
	global_load_dword v3, v1, s[90:91] offset:1792 sc1
	global_load_dword v4, v1, s[90:91] offset:2048 sc1
	global_load_dword v5, v1, s[90:91] offset:2304 sc1
	global_load_dword v6, v1, s[90:91] offset:2560 sc1
	global_load_dword v7, v1, s[90:91] offset:2816 sc1
	global_load_dword v8, v1, s[90:91] offset:3072 sc1
	global_load_dword v9, v1, s[90:91] offset:3328 sc1
	global_load_dword v10, v1, s[90:91] offset:3584 sc1
	global_load_dword v11, v1, s[90:91] offset:3840 sc1
	global_load_dword v12, v1, s[2:3] sc1
	global_load_dword v13, v1, s[4:5] sc1
	global_load_dword v14, v1, s[6:7] sc1
	global_load_dword v15, v1, s[8:9] sc1
	s_mov_b64 s[10:11], -1
	s_mov_b64 s[12:13], -1
	s_waitcnt vmcnt(14)
	v_add_u32_e32 v17, v0, v16
	s_waitcnt vmcnt(13)
	v_add_u32_e32 v17, v17, v2
	s_waitcnt vmcnt(12)
	v_add_u32_e32 v17, v17, v3
	s_waitcnt vmcnt(11)
	v_add_u32_e32 v17, v17, v4
	s_waitcnt vmcnt(10)
	v_add_u32_e32 v17, v17, v5
	s_waitcnt vmcnt(9)
	v_add_u32_e32 v17, v17, v6
	s_waitcnt vmcnt(8)
	v_add_u32_e32 v17, v17, v7
	s_waitcnt vmcnt(7)
	v_add_u32_e32 v17, v17, v8
	s_waitcnt vmcnt(6)
	v_add_u32_e32 v17, v17, v9
	s_waitcnt vmcnt(5)
	v_add_u32_e32 v17, v17, v10
	s_waitcnt vmcnt(4)
	v_add_u32_e32 v17, v17, v11
	s_waitcnt vmcnt(3)
	v_add_u32_e32 v17, v17, v12
	s_waitcnt vmcnt(2)
	v_add_u32_e32 v17, v17, v13
	s_waitcnt vmcnt(1)
	v_add_u32_e32 v17, v17, v14
	s_waitcnt vmcnt(0)
	v_add_u32_e32 v17, v17, v15
	v_cmp_eq_u32_e32 vcc, s23, v17
	s_cbranch_vccnz .LBB0_1023
	s_and_b32 s10, s17, 0xff
	s_cmp_eq_u32 s10, 0
	s_mov_b64 s[10:11], -1
	s_mov_b64 s[14:15], -1
	s_cbranch_scc1 .LBB0_1028
	s_and_b64 vcc, exec, s[14:15]
	s_cbranch_vccz .LBB0_1023

.LBB0_1042:
	s_and_b32 s16, s20, 0xff
	s_mov_b64 s[14:15], -1
	s_cmp_lg_u32 s16, 0
	s_mov_b64 s[18:19], -1
	s_cbranch_scc0 .LBB0_1045
	s_and_b64 vcc, exec, s[18:19]
	s_cbranch_vccz .LBB0_1041

.LBB0_1059:
	s_and_b32 s18, s22, 0xff
	s_mov_b64 s[16:17], -1
	s_cmp_lg_u32 s18, 0
	s_mov_b64 s[20:21], -1
	s_cbranch_scc0 .LBB0_1062
	s_and_b64 vcc, exec, s[20:21]
	s_cbranch_vccz .LBB0_1058
